# k34 + P3 RMSNorm wave sums via DPP (quad_perm/row_mirror/row_bcast) + readlane instead of 6-stage ds_bpermute butterflies
# speedup vs baseline: 1.0182x; 1.0031x over previous
; __device__ __forceinline__ unsigned pk2(float lo, float hi) { return f2bf(lo) | (f2bf(hi) << 16); }
; __device__ __forceinline__ void row_load(const bf16_t* xrow, int lane, f32x4 (&xv)[8]) {
;     const u32x2* xr = (const u32x2*)xrow + lane;
; #pragma unroll
;     for (int j = 0; j < 8; ++j) { const u32x2 w = xr[64 * j]; xv[j] = (f32x4){bflo(w.x), bfhi(w.x), bflo(w.y), bfhi(w.y)}; }
; }
; __device__ __forceinline__ void row_load(const float* xrow, int lane, f32x4 (&xv)[8]) {
;     const f32x4* xr = (const f32x4*)xrow + lane;
; #pragma unroll
;     for (int j = 0; j < 8; ++j) xv[j] = xr[64 * j];
; }
; __device__ __forceinline__ void row_finish(f32x4 (&xv)[8], const f32x4 (&gv)[8], bf16_t* orow, int lane) {
;     float s = 0.f;
; #pragma unroll
;     for (int j = 0; j < 8; ++j) s += (xv[j].x * xv[j].x + xv[j].y * xv[j].y) + (xv[j].z * xv[j].z + xv[j].w * xv[j].w);
;     const float r = 1.0f / sqrtf(wave_sum(s) * (1.0f / D) + RMS_EPS);
;     u32x2* o8 = (u32x2*)orow + lane;
; #pragma unroll
;     for (int j = 0; j < 8; ++j) { xv[j] = xv[j] * r * gv[j]; u32x2 w; w.x = pk2(xv[j].x, xv[j].y); w.y = pk2(xv[j].z, xv[j].w); o8[64 * j] = w; }
; }
.LBB0_200:
	s_waitcnt vmcnt(7)
	v_lshlrev_b32_e32 v86, 16, v84
	v_and_b32_e32 v87, 0xffff0000, v84
	v_lshlrev_b32_e32 v84, 16, v85
	v_and_b32_e32 v85, 0xffff0000, v85
	s_waitcnt vmcnt(6)
	v_lshlrev_b32_e32 v89, 16, v83
	v_lshlrev_b32_e32 v88, 16, v82
	v_and_b32_e32 v83, 0xffff0000, v83
	v_and_b32_e32 v82, 0xffff0000, v82
	s_waitcnt vmcnt(2)
	v_lshlrev_b32_e32 v92, 16, v74
	v_and_b32_e32 v90, 0xffff0000, v74
	s_waitcnt vmcnt(0)
	v_lshlrev_b32_e32 v103, 16, v70
	v_and_b32_e32 v101, 0xffff0000, v70
	v_mul_f32_e32 v70, v85, v85
	v_mul_f32_e32 v74, v87, v87
	v_lshlrev_b32_e32 v107, 16, v78
	v_lshlrev_b32_e32 v93, 16, v75
	v_and_b32_e32 v91, 0xffff0000, v75
	v_lshlrev_b32_e32 v94, 16, v72
	v_and_b32_e32 v95, 0xffff0000, v72
	v_lshlrev_b32_e32 v96, 16, v73
	v_and_b32_e32 v97, 0xffff0000, v73
	v_lshlrev_b32_e32 v98, 16, v71
	v_and_b32_e32 v99, 0xffff0000, v71
	v_pk_fma_f32 v[70:71], v[84:85], v[84:85], v[70:71] op_sel_hi:[1,1,0]
	v_pk_mul_f32 v[72:73], v[82:83], v[82:83]
	v_pk_fma_f32 v[74:75], v[86:87], v[86:87], v[74:75] op_sel_hi:[1,1,0]
	v_and_b32_e32 v109, 0xffff0000, v78
	v_lshlrev_b32_e32 v113, 16, v77
	v_lshlrev_b32_e32 v112, 16, v76
	v_and_b32_e32 v115, 0xffff0000, v77
	v_and_b32_e32 v114, 0xffff0000, v76
	v_pk_fma_f32 v[72:73], v[88:89], v[88:89], v[72:73]
	v_mov_b32_e32 v106, v74
	v_mov_b32_e32 v76, v70
	v_mov_b32_e32 v77, v107
	v_mul_f32_e32 v78, v109, v109
	v_pk_add_f32 v[70:71], v[74:75], v[70:71]
	v_pk_mul_f32 v[74:75], v[106:107], v[76:77]
	v_pk_add_f32 v[72:73], v[72:73], v[72:73] op_sel:[0,1] op_sel_hi:[1,0]
	v_lshlrev_b32_e32 v104, 16, v80
	v_and_b32_e32 v105, 0xffff0000, v80
	v_lshlrev_b32_e32 v80, 16, v81
	v_and_b32_e32 v81, 0xffff0000, v81
	v_mov_b32_e32 v71, v75
	v_mov_b32_e32 v73, v78
	v_lshlrev_b32_e32 v110, 16, v79
	v_and_b32_e32 v111, 0xffff0000, v79
	v_pk_add_f32 v[70:71], v[70:71], v[72:73]
	v_mul_f32_e32 v72, v105, v105
	v_mul_f32_e32 v74, v81, v81
	v_mul_f32_e32 v79, v110, v110
	v_mul_f32_e32 v100, v111, v111
	v_pk_fma_f32 v[72:73], v[104:105], v[104:105], v[72:73] op_sel_hi:[1,1,0]
	v_pk_fma_f32 v[74:75], v[80:81], v[80:81], v[74:75] op_sel_hi:[1,1,0]
	v_mov_b32_e32 v73, v79
	v_mov_b32_e32 v75, v100
	v_pk_add_f32 v[72:73], v[72:73], v[74:75]
	v_pk_mul_f32 v[74:75], v[90:91], v[90:91]
	v_pk_add_f32 v[70:71], v[70:71], v[72:73]
	v_pk_mul_f32 v[72:73], v[114:115], v[114:115]
	v_pk_add_f32 v[70:71], v[70:71], v[70:71] op_sel:[0,1] op_sel_hi:[1,0]
	v_pk_fma_f32 v[72:73], v[112:113], v[112:113], v[72:73]
	v_mov_b32_e32 v102, v70
	v_pk_add_f32 v[72:73], v[72:73], v[72:73] op_sel:[0,1] op_sel_hi:[1,0]
	v_mov_b32_e32 v77, v103
	v_mov_b32_e32 v76, v72
	v_pk_fma_f32 v[74:75], v[92:93], v[92:93], v[74:75]
	v_pk_add_f32 v[70:71], v[70:71], v[72:73]
	v_pk_mul_f32 v[72:73], v[102:103], v[76:77]
	v_mul_f32_e32 v78, v101, v101
	v_mov_b32_e32 v71, v73
	v_pk_add_f32 v[72:73], v[74:75], v[74:75] op_sel:[0,1] op_sel_hi:[1,0]
	v_mul_f32_e32 v74, v97, v97
	v_mov_b32_e32 v73, v78
	v_pk_add_f32 v[70:71], v[70:71], v[72:73]
	v_mul_f32_e32 v72, v95, v95
	v_mul_f32_e32 v79, v98, v98
	v_mul_f32_e32 v100, v99, v99
	v_pk_fma_f32 v[72:73], v[94:95], v[94:95], v[72:73] op_sel_hi:[1,1,0]
	v_pk_fma_f32 v[74:75], v[96:97], v[96:97], v[74:75] op_sel_hi:[1,1,0]
	v_mov_b32_e32 v73, v79
	v_mov_b32_e32 v75, v100
	v_pk_add_f32 v[72:73], v[72:73], v[74:75]
	v_lshl_add_u64 v[116:117], s[16:17], 1, v[34:35]
	v_pk_add_f32 v[70:71], v[70:71], v[72:73]
	v_mov_b32_e32 v108, v107
	v_add_f32_e32 v70, v70, v71
	s_waitcnt lgkmcnt(0)
	s_nop 1
	v_add_f32_dpp v70, v70, v70 quad_perm:[1,0,3,2] row_mask:0xf bank_mask:0xf
	s_nop 1
	v_add_f32_dpp v70, v70, v70 quad_perm:[2,3,0,1] row_mask:0xf bank_mask:0xf
	s_nop 1
	v_add_f32_dpp v70, v70, v70 row_half_mirror row_mask:0xf bank_mask:0xf
	s_nop 1
	v_add_f32_dpp v70, v70, v70 row_mirror row_mask:0xf bank_mask:0xf
	s_nop 1
	v_add_f32_dpp v70, v70, v70 row_bcast:15 row_mask:0xa bank_mask:0xf
	s_nop 1
	v_add_f32_dpp v70, v70, v70 row_bcast:31 row_mask:0xc bank_mask:0xf
	s_nop 1
	v_readlane_b32 s4, v70, 63
	s_nop 3
	v_mov_b32_e32 v70, s4
	v_fmamk_f32 v70, v70, 0x3a000000, v150
	v_mul_f32_e32 v71, 0x4f800000, v70
	v_cmp_gt_f32_e32 vcc, s18, v70
	s_nop 1
	v_cndmask_b32_e32 v70, v70, v71, vcc
	v_sqrt_f32_e32 v71, v70
	s_nop 0
	v_add_u32_e32 v72, -1, v71
	v_fma_f32 v73, -v72, v71, v70
	v_cmp_ge_f32_e64 s[4:5], 0, v73
	v_add_u32_e32 v73, 1, v71
	s_nop 0
	v_cndmask_b32_e64 v72, v71, v72, s[4:5]
	v_fma_f32 v71, -v73, v71, v70
	v_cmp_lt_f32_e64 s[4:5], 0, v71
	s_nop 1
	v_cndmask_b32_e64 v71, v72, v73, s[4:5]
	v_mul_f32_e32 v72, 0x37800000, v71
	v_cndmask_b32_e32 v71, v71, v72, vcc
	v_cmp_class_f32_e32 vcc, v70, v151
	s_nop 1
	v_cndmask_b32_e32 v70, v71, v70, vcc
	v_div_scale_f32 v71, s[4:5], v70, v70, 1.0
	v_rcp_f32_e32 v72, v71
	s_nop 0
	v_fma_f32 v73, -v71, v72, 1.0
	v_fmac_f32_e32 v72, v73, v72
	v_div_scale_f32 v73, vcc, 1.0, v70, 1.0
	v_mul_f32_e32 v74, v73, v72
	v_fma_f32 v75, -v71, v74, v73
	v_fmac_f32_e32 v74, v75, v72
	v_fma_f32 v71, -v71, v74, v73
	v_div_fmas_f32 v71, v71, v72, v74
	v_div_fixup_f32 v102, v71, v70, 1.0
	v_pk_mul_f32 v[72:73], v[102:103], v[86:87] op_sel_hi:[0,1]
	v_pk_mul_f32 v[72:73], v[0:1], v[72:73]
	v_pk_mul_f32 v[70:71], v[102:103], v[84:85] op_sel_hi:[0,1]
	v_bfe_u32 v74, v72, 16, 1
	v_add3_u32 v74, v72, v74, s19
	v_bfe_u32 v75, v73, 16, 1
	v_pk_mul_f32 v[70:71], v[2:3], v[70:71]
	v_lshrrev_b32_e32 v74, 16, v74
	v_add3_u32 v75, v73, v75, s19
	v_and_or_b32 v74, v75, s9, v74
	v_bfe_u32 v75, v70, 16, 1
	v_add3_u32 v75, v70, v75, s19
	v_bfe_u32 v76, v71, 16, 1
	v_lshrrev_b32_e32 v75, 16, v75
	v_add3_u32 v76, v71, v76, s19
	v_and_or_b32 v75, v76, s9, v75
	global_store_dwordx2 v[116:117], v[74:75], off
; __device__ __forceinline__ unsigned pk2(float lo, float hi) { return f2bf(lo) | (f2bf(hi) << 16); }
; __device__ __forceinline__ void row_finish(f32x4 (&xv)[8], const f32x4 (&gv)[8], bf16_t* orow, int lane) {
;     ...
;     u32x2* o8 = (u32x2*)orow + lane;
; #pragma unroll
;     for (int j = 0; j < 8; ++j) { xv[j] = xv[j] * r * gv[j]; u32x2 w; w.x = pk2(xv[j].x, xv[j].y); w.y = pk2(xv[j].z, xv[j].w); o8[64 * j] = w; }
; __global__ void __launch_bounds__(NWAVES * 64, 2) fwd_megakernel(Args args) {
;     ...
;             if (two) row_finish(h1, gv, H + (size_t)m1 * D, F.lane);
	v_mov_b32_e32 v74, v88
	v_mov_b32_e32 v75, v82
	v_pk_mul_f32 v[76:77], v[102:103], v[74:75] op_sel_hi:[0,1]
	v_pk_mul_f32 v[76:77], v[4:5], v[76:77]
	v_mov_b32_e32 v82, v89
	v_bfe_u32 v78, v76, 16, 1
	v_pk_mul_f32 v[74:75], v[102:103], v[82:83] op_sel_hi:[0,1]
	v_add3_u32 v78, v76, v78, s19
	v_bfe_u32 v79, v77, 16, 1
	v_pk_mul_f32 v[74:75], v[6:7], v[74:75]
	v_lshrrev_b32_e32 v78, 16, v78
	v_add3_u32 v79, v77, v79, s19
	v_and_or_b32 v78, v79, s9, v78
	v_bfe_u32 v79, v74, 16, 1
	v_add3_u32 v79, v74, v79, s19
	v_bfe_u32 v82, v75, 16, 1
	v_lshrrev_b32_e32 v79, 16, v79
	v_add3_u32 v82, v75, v82, s19
	v_and_or_b32 v79, v82, s9, v79
	v_pk_mul_f32 v[82:83], v[102:103], v[104:105] op_sel_hi:[0,1]
	global_store_dwordx2 v[116:117], v[78:79], off offset:512
	v_pk_mul_f32 v[78:79], v[102:103], v[80:81] op_sel_hi:[0,1]
	v_pk_mul_f32 v[80:81], v[8:9], v[82:83]
	v_pk_mul_f32 v[78:79], v[10:11], v[78:79]
	v_bfe_u32 v82, v80, 16, 1
	v_add3_u32 v82, v80, v82, s19
	v_bfe_u32 v83, v81, 16, 1
	v_lshrrev_b32_e32 v82, 16, v82
	v_add3_u32 v83, v81, v83, s19
	v_and_or_b32 v82, v83, s9, v82
	v_bfe_u32 v83, v78, 16, 1
	v_add3_u32 v83, v78, v83, s19
	v_bfe_u32 v84, v79, 16, 1
	v_lshrrev_b32_e32 v83, 16, v83
	v_add3_u32 v84, v79, v84, s19
	v_and_or_b32 v83, v84, s9, v83
	v_pk_mul_f32 v[84:85], v[108:109], v[102:103] op_sel_hi:[1,0]
	global_store_dwordx2 v[116:117], v[82:83], off offset:1024
	v_pk_mul_f32 v[84:85], v[12:13], v[84:85]
	v_pk_mul_f32 v[82:83], v[110:111], v[102:103] op_sel_hi:[1,0]
	v_bfe_u32 v86, v84, 16, 1
	v_add3_u32 v86, v84, v86, s19
	v_bfe_u32 v87, v85, 16, 1
	v_pk_mul_f32 v[82:83], v[14:15], v[82:83]
	v_lshrrev_b32_e32 v86, 16, v86
	v_add3_u32 v87, v85, v87, s19
	v_and_or_b32 v86, v87, s9, v86
	v_bfe_u32 v87, v82, 16, 1
	v_add3_u32 v87, v82, v87, s19
	v_bfe_u32 v88, v83, 16, 1
	v_lshrrev_b32_e32 v87, 16, v87
	v_add3_u32 v88, v83, v88, s19
	v_and_or_b32 v87, v88, s9, v87
	global_store_dwordx2 v[116:117], v[86:87], off offset:1536
	v_mov_b32_e32 v86, v112
	v_mov_b32_e32 v87, v114
	v_pk_mul_f32 v[88:89], v[102:103], v[86:87] op_sel_hi:[0,1]
	v_pk_mul_f32 v[88:89], v[16:17], v[88:89]
	v_mov_b32_e32 v114, v113
	v_bfe_u32 v100, v88, 16, 1
	v_pk_mul_f32 v[86:87], v[102:103], v[114:115] op_sel_hi:[0,1]
	v_add3_u32 v100, v88, v100, s19
	v_bfe_u32 v104, v89, 16, 1
	v_pk_mul_f32 v[86:87], v[18:19], v[86:87]
	v_lshrrev_b32_e32 v100, 16, v100
	v_add3_u32 v104, v89, v104, s19
	v_and_or_b32 v104, v104, s9, v100
	v_bfe_u32 v100, v86, 16, 1
	v_add3_u32 v100, v86, v100, s19
	v_bfe_u32 v105, v87, 16, 1
	v_lshrrev_b32_e32 v100, 16, v100
	v_add3_u32 v105, v87, v105, s19
	v_and_or_b32 v105, v105, s9, v100
	global_store_dwordx2 v[116:117], v[104:105], off offset:2048
	v_mov_b32_e32 v104, v92
	v_mov_b32_e32 v105, v90
	v_pk_mul_f32 v[104:105], v[102:103], v[104:105] op_sel_hi:[0,1]
	v_mov_b32_e32 v90, v93
	v_pk_mul_f32 v[92:93], v[20:21], v[104:105]
	v_pk_mul_f32 v[90:91], v[102:103], v[90:91] op_sel_hi:[0,1]
	v_bfe_u32 v100, v92, 16, 1
	v_add3_u32 v100, v92, v100, s19
	v_bfe_u32 v104, v93, 16, 1
	v_pk_mul_f32 v[90:91], v[22:23], v[90:91]
	v_lshrrev_b32_e32 v100, 16, v100
	v_add3_u32 v104, v93, v104, s19
	v_and_or_b32 v104, v104, s9, v100
	v_bfe_u32 v100, v90, 16, 1
	v_add3_u32 v100, v90, v100, s19
	v_bfe_u32 v105, v91, 16, 1
	v_lshrrev_b32_e32 v100, 16, v100
	v_add3_u32 v105, v91, v105, s19
	v_and_or_b32 v105, v105, s9, v100
	global_store_dwordx2 v[116:117], v[104:105], off offset:2560
	v_pk_mul_f32 v[104:105], v[102:103], v[94:95] op_sel_hi:[0,1]
	v_pk_mul_f32 v[94:95], v[102:103], v[96:97] op_sel_hi:[0,1]
	v_pk_mul_f32 v[96:97], v[24:25], v[104:105]
	v_pk_mul_f32 v[94:95], v[26:27], v[94:95]
	v_bfe_u32 v100, v96, 16, 1
	v_add3_u32 v100, v96, v100, s19
	v_bfe_u32 v104, v97, 16, 1
	v_lshrrev_b32_e32 v100, 16, v100
	v_add3_u32 v104, v97, v104, s19
	v_and_or_b32 v104, v104, s9, v100
	v_bfe_u32 v100, v94, 16, 1
	v_add3_u32 v100, v94, v100, s19
	v_bfe_u32 v105, v95, 16, 1
	v_lshrrev_b32_e32 v100, 16, v100
	v_add3_u32 v105, v95, v105, s19
	v_and_or_b32 v105, v105, s9, v100
	v_mov_b32_e32 v100, v103
	v_pk_mul_f32 v[100:101], v[100:101], v[102:103] op_sel_hi:[1,0]
	v_pk_mul_f32 v[98:99], v[98:99], v[102:103] op_sel_hi:[1,0]
	v_pk_mul_f32 v[100:101], v[28:29], v[100:101]
	v_pk_mul_f32 v[98:99], v[30:31], v[98:99]
	v_bfe_u32 v102, v100, 16, 1
	v_add3_u32 v102, v100, v102, s19
	v_bfe_u32 v103, v101, 16, 1
	v_lshrrev_b32_e32 v102, 16, v102
	v_add3_u32 v103, v101, v103, s19
	v_and_or_b32 v102, v103, s9, v102
	v_bfe_u32 v103, v98, 16, 1
	global_store_dwordx2 v[116:117], v[104:105], off offset:3072
	v_add3_u32 v103, v98, v103, s19
	v_bfe_u32 v104, v99, 16, 1
	v_lshrrev_b32_e32 v103, 16, v103
	v_add3_u32 v104, v99, v104, s19
	v_and_or_b32 v103, v104, s9, v103
	v_cndmask_b32_e64 v104, 0, 1, s[6:7]
	v_cmp_ne_u32_e64 s[4:5], 1, v104
	s_andn2_b64 vcc, exec, s[6:7]
	global_store_dwordx2 v[116:117], v[102:103], off offset:3584
	s_cbranch_vccnz .LBB0_202
; __device__ __forceinline__ void row_finish(f32x4 (&xv)[8], const f32x4 (&gv)[8], bf16_t* orow, int lane) {
;     float s = 0.f;
; #pragma unroll
;     for (int j = 0; j < 8; ++j) s += (xv[j].x * xv[j].x + xv[j].y * xv[j].y) + (xv[j].z * xv[j].z + xv[j].w * xv[j].w);
;     const float r = 1.0f / sqrtf(wave_sum(s) * (1.0f / D) + RMS_EPS);
	v_pk_mul_f32 v[110:111], v[40:41], v[40:41]
	v_pk_mul_f32 v[112:113], v[44:45], v[44:45]
	v_pk_mul_f32 v[114:115], v[42:43], v[42:43]
	v_pk_mul_f32 v[116:117], v[38:39], v[38:39]
	v_pk_mul_f32 v[106:107], v[48:49], v[48:49]
	v_pk_mul_f32 v[108:109], v[46:47], v[46:47]
	v_mov_b32_e32 v118, v116
	v_mov_b32_e32 v119, v114
	v_mov_b32_e32 v114, v117
	v_mov_b32_e32 v116, v110
	v_mov_b32_e32 v117, v112
	v_mov_b32_e32 v112, v111
	v_pk_add_f32 v[110:111], v[116:117], v[112:113]
	v_pk_mov_b32 v[112:113], v[108:109], v[106:107] op_sel:[1,0]
	v_mov_b32_e32 v109, v107
	v_pk_add_f32 v[106:107], v[112:113], v[108:109]
	v_pk_add_f32 v[114:115], v[118:119], v[114:115]
	v_pk_add_f32 v[106:107], v[106:107], v[106:107] op_sel_hi:[0,1]
	v_mul_f32_e32 v106, v50, v50
	v_pk_add_f32 v[110:111], v[114:115], v[110:111]
	v_pk_fma_f32 v[108:109], v[50:51], v[50:51], v[106:107] op_sel_hi:[1,1,0]
	v_mul_f32_e32 v106, v52, v52
	v_pk_add_f32 v[110:111], v[110:111], v[110:111] op_sel_hi:[0,1]
	v_pk_fma_f32 v[112:113], v[52:53], v[52:53], v[106:107] op_sel_hi:[1,1,0]
	v_mul_f32_e32 v108, v54, v54
	v_mul_f32_e32 v112, v55, v55
	v_mul_f32_e32 v106, v56, v56
	v_mul_f32_e32 v110, v57, v57
	v_pk_mul_f32 v[102:103], v[60:61], v[60:61]
	v_pk_mul_f32 v[104:105], v[58:59], v[58:59]
	v_pk_add_f32 v[108:109], v[108:109], v[112:113]
	v_pk_add_f32 v[106:107], v[106:107], v[110:111]
	s_ashr_i32 s15, s14, 31
	v_pk_add_f32 v[106:107], v[108:109], v[106:107]
	v_pk_mov_b32 v[108:109], v[104:105], v[102:103] op_sel:[1,0]
	v_mov_b32_e32 v105, v103
	v_pk_add_f32 v[102:103], v[108:109], v[104:105]
	v_pk_add_f32 v[106:107], v[106:107], v[106:107] op_sel_hi:[0,1]
	v_pk_add_f32 v[102:103], v[102:103], v[102:103] op_sel_hi:[0,1]
	v_mul_f32_e32 v102, v62, v62
	v_pk_fma_f32 v[104:105], v[62:63], v[62:63], v[102:103] op_sel_hi:[1,1,0]
	v_mul_f32_e32 v102, v64, v64
	v_pk_fma_f32 v[108:109], v[64:65], v[64:65], v[102:103] op_sel_hi:[1,1,0]
	v_mul_f32_e32 v104, v66, v66
	v_mul_f32_e32 v108, v67, v67
	v_mul_f32_e32 v102, v68, v68
	v_mul_f32_e32 v106, v69, v69
	v_pk_add_f32 v[104:105], v[104:105], v[108:109]
	v_pk_add_f32 v[102:103], v[102:103], v[106:107]
	s_nop 0
	v_pk_add_f32 v[102:103], v[104:105], v[102:103]
	s_nop 0
	v_add_f32_e32 v102, v102, v103
	s_waitcnt lgkmcnt(0)
; __device__ __forceinline__ unsigned pk2(float lo, float hi) { return f2bf(lo) | (f2bf(hi) << 16); }
; __device__ __forceinline__ void row_finish(f32x4 (&xv)[8], const f32x4 (&gv)[8], bf16_t* orow, int lane) {
;     ...
;     const float r = 1.0f / sqrtf(wave_sum(s) * (1.0f / D) + RMS_EPS);
;     u32x2* o8 = (u32x2*)orow + lane;
; #pragma unroll
;     for (int j = 0; j < 8; ++j) { xv[j] = xv[j] * r * gv[j]; u32x2 w; w.x = pk2(xv[j].x, xv[j].y); w.y = pk2(xv[j].z, xv[j].w); o8[64 * j] = w; }
	s_nop 1
	v_add_f32_dpp v102, v102, v102 quad_perm:[1,0,3,2] row_mask:0xf bank_mask:0xf
	s_nop 1
	v_add_f32_dpp v102, v102, v102 quad_perm:[2,3,0,1] row_mask:0xf bank_mask:0xf
	s_nop 1
	v_add_f32_dpp v102, v102, v102 row_half_mirror row_mask:0xf bank_mask:0xf
	s_nop 1
	v_add_f32_dpp v102, v102, v102 row_mirror row_mask:0xf bank_mask:0xf
	s_nop 1
	v_add_f32_dpp v102, v102, v102 row_bcast:15 row_mask:0xa bank_mask:0xf
	s_nop 1
	v_add_f32_dpp v102, v102, v102 row_bcast:31 row_mask:0xc bank_mask:0xf
	s_nop 1
	v_readlane_b32 s6, v102, 63
	s_nop 3
	v_mov_b32_e32 v102, s6
	v_fmamk_f32 v102, v102, 0x3a000000, v150
	v_mul_f32_e32 v103, 0x4f800000, v102
	v_cmp_gt_f32_e32 vcc, s18, v102
	s_nop 1
	v_cndmask_b32_e32 v102, v102, v103, vcc
	v_sqrt_f32_e32 v103, v102
	s_nop 0
	v_add_u32_e32 v104, -1, v103
	v_fma_f32 v105, -v104, v103, v102
	v_cmp_ge_f32_e64 s[6:7], 0, v105
	v_add_u32_e32 v105, 1, v103
	s_nop 0
	v_cndmask_b32_e64 v104, v103, v104, s[6:7]
	v_fma_f32 v103, -v105, v103, v102
	v_cmp_lt_f32_e64 s[6:7], 0, v103
	s_nop 1
	v_cndmask_b32_e64 v103, v104, v105, s[6:7]
	v_mul_f32_e32 v104, 0x37800000, v103
	v_cndmask_b32_e32 v103, v103, v104, vcc
	v_cmp_class_f32_e32 vcc, v102, v151
	s_nop 1
	v_cndmask_b32_e32 v102, v103, v102, vcc
	v_div_scale_f32 v103, s[6:7], v102, v102, 1.0
	v_rcp_f32_e32 v104, v103
	s_lshl_b64 s[6:7], s[14:15], 12
	v_fma_f32 v105, -v103, v104, 1.0
	v_fmac_f32_e32 v104, v105, v104
	v_div_scale_f32 v105, vcc, 1.0, v102, 1.0
	v_mul_f32_e32 v106, v105, v104
	v_fma_f32 v107, -v103, v106, v105
	v_fmac_f32_e32 v106, v107, v104
	v_fma_f32 v103, -v103, v106, v105
	v_div_fmas_f32 v103, v103, v104, v106
	v_div_fixup_f32 v102, v103, v102, 1.0
	v_pk_mul_f32 v[38:39], v[38:39], v[102:103] op_sel_hi:[1,0]
	v_pk_mul_f32 v[40:41], v[40:41], v[102:103] op_sel_hi:[1,0]
	v_pk_mul_f32 v[38:39], v[0:1], v[38:39]
	v_pk_mul_f32 v[40:41], v[2:3], v[40:41]
	v_bfe_u32 v103, v38, 16, 1
	v_add3_u32 v103, v38, v103, s19
	v_bfe_u32 v106, v39, 16, 1
	v_lshrrev_b32_e32 v103, 16, v103
	v_add3_u32 v106, v39, v106, s19
	v_and_or_b32 v106, v106, s9, v103
	v_bfe_u32 v103, v40, 16, 1
	v_add3_u32 v103, v40, v103, s19
	v_lshrrev_b32_e32 v103, 16, v103
	v_bfe_u32 v107, v41, 16, 1
	v_pk_mul_f32 v[42:43], v[42:43], v[102:103] op_sel_hi:[1,0]
	v_add3_u32 v107, v41, v107, s19
	v_pk_mul_f32 v[42:43], v[4:5], v[42:43]
	v_lshl_add_u64 v[104:105], v[34:35], 0, s[6:7]
	v_and_or_b32 v107, v107, s9, v103
	v_pk_mul_f32 v[44:45], v[44:45], v[102:103] op_sel_hi:[1,0]
	v_bfe_u32 v103, v42, 16, 1
	global_store_dwordx2 v[104:105], v[106:107], off
	v_add3_u32 v103, v42, v103, s19
	v_bfe_u32 v106, v43, 16, 1
	v_pk_mul_f32 v[44:45], v[6:7], v[44:45]
	v_lshrrev_b32_e32 v103, 16, v103
	v_add3_u32 v106, v43, v106, s19
	v_and_or_b32 v106, v106, s9, v103
	v_bfe_u32 v103, v44, 16, 1
	v_add3_u32 v103, v44, v103, s19
	v_lshrrev_b32_e32 v103, 16, v103
	v_bfe_u32 v107, v45, 16, 1
	v_pk_mul_f32 v[46:47], v[46:47], v[102:103] op_sel_hi:[1,0]
	v_add3_u32 v107, v45, v107, s19
	v_pk_mul_f32 v[46:47], v[8:9], v[46:47]
	v_and_or_b32 v107, v107, s9, v103
	v_pk_mul_f32 v[48:49], v[48:49], v[102:103] op_sel_hi:[1,0]
	v_bfe_u32 v103, v46, 16, 1
	global_store_dwordx2 v[104:105], v[106:107], off offset:512
	v_add3_u32 v103, v46, v103, s19
	v_bfe_u32 v106, v47, 16, 1
	v_pk_mul_f32 v[48:49], v[10:11], v[48:49]
	v_lshrrev_b32_e32 v103, 16, v103
	v_add3_u32 v106, v47, v106, s19
	v_and_or_b32 v106, v106, s9, v103
	v_bfe_u32 v103, v48, 16, 1
	v_add3_u32 v103, v48, v103, s19
	v_lshrrev_b32_e32 v103, 16, v103
	v_bfe_u32 v107, v49, 16, 1
	v_pk_mul_f32 v[50:51], v[50:51], v[102:103] op_sel_hi:[1,0]
	v_add3_u32 v107, v49, v107, s19
	v_pk_mul_f32 v[50:51], v[12:13], v[50:51]
	v_and_or_b32 v107, v107, s9, v103
	v_pk_mul_f32 v[52:53], v[52:53], v[102:103] op_sel_hi:[1,0]
	v_bfe_u32 v103, v50, 16, 1
	global_store_dwordx2 v[104:105], v[106:107], off offset:1024
	v_add3_u32 v103, v50, v103, s19
	v_bfe_u32 v106, v51, 16, 1
	v_pk_mul_f32 v[52:53], v[14:15], v[52:53]
	v_lshrrev_b32_e32 v103, 16, v103
	v_add3_u32 v106, v51, v106, s19
	v_and_or_b32 v106, v106, s9, v103
	v_bfe_u32 v103, v52, 16, 1
	v_add3_u32 v103, v52, v103, s19
	v_lshrrev_b32_e32 v103, 16, v103
	v_bfe_u32 v107, v53, 16, 1
	v_pk_mul_f32 v[54:55], v[54:55], v[102:103] op_sel_hi:[1,0]
	v_add3_u32 v107, v53, v107, s19
	v_pk_mul_f32 v[54:55], v[16:17], v[54:55]
	v_and_or_b32 v107, v107, s9, v103
	v_pk_mul_f32 v[56:57], v[56:57], v[102:103] op_sel_hi:[1,0]
	v_bfe_u32 v103, v54, 16, 1
	global_store_dwordx2 v[104:105], v[106:107], off offset:1536
	v_add3_u32 v103, v54, v103, s19
	v_bfe_u32 v106, v55, 16, 1
	v_pk_mul_f32 v[56:57], v[18:19], v[56:57]
	v_lshrrev_b32_e32 v103, 16, v103
	v_add3_u32 v106, v55, v106, s19
	v_and_or_b32 v106, v106, s9, v103
	v_bfe_u32 v103, v56, 16, 1
	v_add3_u32 v103, v56, v103, s19
	v_lshrrev_b32_e32 v103, 16, v103
	v_bfe_u32 v107, v57, 16, 1
	v_pk_mul_f32 v[58:59], v[58:59], v[102:103] op_sel_hi:[1,0]
	v_add3_u32 v107, v57, v107, s19
	v_pk_mul_f32 v[58:59], v[20:21], v[58:59]
	v_and_or_b32 v107, v107, s9, v103
	v_pk_mul_f32 v[60:61], v[60:61], v[102:103] op_sel_hi:[1,0]
	v_bfe_u32 v103, v58, 16, 1
	global_store_dwordx2 v[104:105], v[106:107], off offset:2048
	v_add3_u32 v103, v58, v103, s19
	v_bfe_u32 v106, v59, 16, 1
	v_pk_mul_f32 v[60:61], v[22:23], v[60:61]
	v_lshrrev_b32_e32 v103, 16, v103
	v_add3_u32 v106, v59, v106, s19
	v_and_or_b32 v106, v106, s9, v103
	v_bfe_u32 v103, v60, 16, 1
	v_add3_u32 v103, v60, v103, s19
	v_lshrrev_b32_e32 v103, 16, v103
	v_bfe_u32 v107, v61, 16, 1
	v_pk_mul_f32 v[62:63], v[62:63], v[102:103] op_sel_hi:[1,0]
	v_add3_u32 v107, v61, v107, s19
	v_pk_mul_f32 v[62:63], v[24:25], v[62:63]
	v_and_or_b32 v107, v107, s9, v103
	v_pk_mul_f32 v[64:65], v[64:65], v[102:103] op_sel_hi:[1,0]
	v_bfe_u32 v103, v62, 16, 1
	global_store_dwordx2 v[104:105], v[106:107], off offset:2560
	v_add3_u32 v103, v62, v103, s19
	v_bfe_u32 v106, v63, 16, 1
	v_pk_mul_f32 v[64:65], v[26:27], v[64:65]
	v_lshrrev_b32_e32 v103, 16, v103
	v_add3_u32 v106, v63, v106, s19
	v_and_or_b32 v106, v106, s9, v103
	v_bfe_u32 v103, v64, 16, 1
	v_add3_u32 v103, v64, v103, s19
	v_lshrrev_b32_e32 v103, 16, v103
	v_pk_mul_f32 v[66:67], v[66:67], v[102:103] op_sel_hi:[1,0]
	v_bfe_u32 v107, v65, 16, 1
	v_pk_mul_f32 v[66:67], v[28:29], v[66:67]
	v_add3_u32 v107, v65, v107, s19
	v_pk_mul_f32 v[68:69], v[68:69], v[102:103] op_sel_hi:[1,0]
	v_bfe_u32 v102, v66, 16, 1
	v_and_or_b32 v107, v107, s9, v103
	v_add3_u32 v102, v66, v102, s19
	v_bfe_u32 v103, v67, 16, 1
	v_pk_mul_f32 v[68:69], v[30:31], v[68:69]
	v_lshrrev_b32_e32 v102, 16, v102
	v_add3_u32 v103, v67, v103, s19
	v_and_or_b32 v102, v103, s9, v102
	v_bfe_u32 v103, v68, 16, 1
	global_store_dwordx2 v[104:105], v[106:107], off offset:3072
	v_add3_u32 v103, v68, v103, s19
	v_bfe_u32 v106, v69, 16, 1
	v_lshrrev_b32_e32 v103, 16, v103
	v_add3_u32 v106, v69, v106, s19
	v_and_or_b32 v103, v106, s9, v103
	global_store_dwordx2 v[104:105], v[102:103], off offset:3584
